# MLA: waves 4-7 issue the next tile's LDS-DMA pieces after block 0 instead of at the loop top (de-phases the two waves per SIMD), on top of rotated loop v31
# baseline (speedup 1.0000x reference)
.LBB0_473:
	s_cmp_lt_u32 s88, 0x100
	s_cbranch_scc0 .LBB0_481
	s_and_b32 s52, s28, 1
	s_mul_i32 s53, s52, 0x6000
	s_add_i32 s53, s53, 0
	s_add_i32 s54, s53, s47
	s_mov_b64 s[12:13], -1
	s_and_b64 vcc, exec, s[2:3]
	s_cbranch_vccnz .LBB0_485
	s_andn2_b64 vcc, exec, s[12:13]
	s_cbranch_vccz .LBB0_486

.LBB0_481:
	s_and_b32 s12, s29, 1
	s_mul_i32 s13, s12, 0x6000
	v_add_u32_e32 v242, s13, v237
	v_lshl_add_u32 v241, s12, 14, v238
	v_add_u32_e32 v232, v241, v240
	v_add_u32_e32 v241, v241, v239
	s_waitcnt lgkmcnt(13)
	v_mfma_f32_32x32x16_bf16 v[112:127], v[144:147], v[184:187], v[64:79]
	v_exp_f32_e32 v80, v80
	v_exp_f32_e32 v81, v81
	v_add_f32_e32 v244, v244, v80
	v_add_f32_e32 v244, v244, v81
	v_cvt_pk_bf16_f32 v80, v80, v81
	v_mfma_f32_32x32x16_bf16 v[128:143], v[144:147], v[200:203], v[64:79]
	ds_read_b128 v[144:147], v242 offset:12288
	v_exp_f32_e32 v82, v82
	v_exp_f32_e32 v83, v83
	v_add_f32_e32 v244, v244, v82
	v_add_f32_e32 v244, v244, v83
	v_cvt_pk_bf16_f32 v81, v82, v83
	s_waitcnt lgkmcnt(13)
	v_mfma_f32_32x32x16_bf16 v[112:127], v[148:151], v[188:191], v[112:127]
	v_exp_f32_e32 v84, v84
	v_exp_f32_e32 v85, v85
	v_add_f32_e32 v244, v244, v84
	v_add_f32_e32 v244, v244, v85
	v_cvt_pk_bf16_f32 v82, v84, v85
	v_mfma_f32_32x32x16_bf16 v[128:143], v[148:151], v[204:207], v[128:143]
	ds_read_b128 v[148:151], v242 offset:13312
	v_exp_f32_e32 v86, v86
	v_exp_f32_e32 v87, v87
	v_add_f32_e32 v244, v244, v86
	v_add_f32_e32 v244, v244, v87
	s_waitcnt lgkmcnt(13)
	v_mfma_f32_32x32x16_bf16 v[112:127], v[152:155], v[192:195], v[112:127]
	v_cvt_pk_bf16_f32 v83, v86, v87
	v_exp_f32_e32 v96, v96
	v_exp_f32_e32 v97, v97
	v_add_f32_e32 v245, v245, v96
	v_mfma_f32_32x32x16_bf16 v[128:143], v[152:155], v[208:211], v[128:143]
	ds_read_b128 v[152:155], v242 offset:14336
	v_add_f32_e32 v245, v245, v97
	v_cvt_pk_bf16_f32 v96, v96, v97
	v_exp_f32_e32 v98, v98
	v_exp_f32_e32 v99, v99
	s_waitcnt lgkmcnt(9)
	v_mfma_f32_32x32x16_bf16 v[48:63], v[80:83], v[168:171], v[48:63]
	v_add_f32_e32 v245, v245, v98
	v_add_f32_e32 v245, v245, v99
	v_cvt_pk_bf16_f32 v97, v98, v99
	v_exp_f32_e32 v100, v100
	v_exp_f32_e32 v101, v101
	v_mfma_f32_32x32x16_bf16 v[112:127], v[156:159], v[196:199], v[112:127]
	v_add_f32_e32 v245, v245, v100
	v_add_f32_e32 v245, v245, v101
	v_cvt_pk_bf16_f32 v98, v100, v101
	v_exp_f32_e32 v102, v102
	v_exp_f32_e32 v103, v103
	s_waitcnt lgkmcnt(7)
	v_mfma_f32_32x32x16_bf16 v[32:47], v[80:83], v[176:179], v[32:47]
	v_add_f32_e32 v245, v245, v102
	v_add_f32_e32 v245, v245, v103
	v_cvt_pk_bf16_f32 v99, v102, v103
	v_exp_f32_e32 v88, v88
	v_mfma_f32_32x32x16_bf16 v[128:143], v[156:159], v[212:215], v[128:143]
	ds_read_b128 v[156:159], v242 offset:15360
	v_exp_f32_e32 v89, v89
	v_add_f32_e32 v244, v244, v88
	v_add_f32_e32 v244, v244, v89
	v_cvt_pk_bf16_f32 v88, v88, v89
	v_mfma_f32_32x32x16_bf16 v[112:127], v[160:163], v[216:219], v[112:127]
	v_exp_f32_e32 v90, v90
	v_exp_f32_e32 v91, v91
	v_add_f32_e32 v244, v244, v90
	v_add_f32_e32 v244, v244, v91
	v_cvt_pk_bf16_f32 v89, v90, v91
	v_mfma_f32_32x32x16_bf16 v[128:143], v[160:163], v[224:227], v[128:143]
	ds_read_b128 v[160:163], v242 offset:16384
	v_exp_f32_e32 v92, v92
	v_exp_f32_e32 v93, v93
	v_add_f32_e32 v244, v244, v92
	v_add_f32_e32 v244, v244, v93
	v_cvt_pk_bf16_f32 v90, v92, v93
	v_mfma_f32_32x32x16_bf16 v[16:31], v[96:99], v[168:171], v[16:31]
	v_exp_f32_e32 v94, v94
	v_exp_f32_e32 v95, v95
	v_add_f32_e32 v244, v244, v94
	v_add_f32_e32 v244, v244, v95
	v_mfma_f32_32x32x16_bf16 v[112:127], v[164:167], v[220:223], v[112:127]
	v_cvt_pk_bf16_f32 v91, v94, v95
	v_exp_f32_e32 v104, v104
	v_exp_f32_e32 v105, v105
	v_add_f32_e32 v245, v245, v104
	v_mfma_f32_32x32x16_bf16 v[0:15], v[96:99], v[176:179], v[0:15]
	v_add_f32_e32 v245, v245, v105
	v_cvt_pk_bf16_f32 v104, v104, v105
	v_exp_f32_e32 v106, v106
	v_exp_f32_e32 v107, v107
	v_add_f32_e32 v245, v245, v106
	v_mfma_f32_32x32x16_bf16 v[128:143], v[164:167], v[228:231], v[128:143]
	ds_read_b128 v[164:167], v242 offset:17408
	v_add_f32_e32 v245, v245, v107
	v_cvt_pk_bf16_f32 v105, v106, v107
	v_exp_f32_e32 v108, v108
	v_exp_f32_e32 v109, v109
	v_add_f32_e32 v245, v245, v108
	s_waitcnt lgkmcnt(8)
	v_mfma_f32_32x32x16_bf16 v[48:63], v[88:91], v[172:175], v[48:63]
	v_add_f32_e32 v245, v245, v109
	v_cvt_pk_bf16_f32 v106, v108, v109
	v_exp_f32_e32 v110, v110
	v_exp_f32_e32 v111, v111
	s_waitcnt lgkmcnt(6)
	v_mfma_f32_32x32x16_bf16 v[32:47], v[88:91], v[180:183], v[32:47]
	v_add_f32_e32 v245, v245, v110
	v_add_f32_e32 v245, v245, v111
	v_cvt_pk_bf16_f32 v107, v110, v111
	ds_read_b64_tr_b16 v[168:169], v241 offset:53248
	ds_read_b64_tr_b16 v[170:171], v241 offset:54272
	ds_read_b64_tr_b16 v[176:177], v232 offset:53248
	ds_read_b64_tr_b16 v[178:179], v232 offset:54272
	v_mfma_f32_32x32x16_bf16 v[16:31], v[104:107], v[172:175], v[16:31]
	ds_read_b64_tr_b16 v[172:173], v241 offset:55296
	ds_read_b64_tr_b16 v[174:175], v241 offset:56320
	v_mfma_f32_32x32x16_bf16 v[0:15], v[104:107], v[180:183], v[0:15]
	ds_read_b64_tr_b16 v[180:181], v232 offset:55296
	ds_read_b64_tr_b16 v[182:183], v232 offset:56320
	s_cmp_lt_u32 s88, 0x100
	s_cbranch_scc1 .Ld2_skip
	s_cmp_eq_u32 s29, 63
	s_cbranch_scc1 .Ld2_skip

.Ld2_480:
	s_lshl_b32 s12, s52, 14
	s_add_i32 s52, s12, 0xc000
	s_add_u32 s53, s96, s26
	s_addc_u32 s54, s91, s27
	s_add_u32 s12, s53, 0x1d220080
	s_addc_u32 s13, s54, 0
	s_add_i32 s55, s52, s50
	s_add_i32 s55, s55, 0
	s_mov_b32 s56, m0
	s_mov_b32 m0, s55
	s_nop 0
	global_load_lds_dwordx4 v236, s[12:13]
	s_mov_b32 m0, s56
	s_add_u32 s12, s53, 0x1d230080
	s_addc_u32 s13, s54, 0
	s_add_i32 s52, s52, s51
	s_add_i32 s52, s52, 0
	s_mov_b32 s53, m0
	s_mov_b32 m0, s52
	s_nop 0
	global_load_lds_dwordx4 v236, s[12:13]
	s_mov_b32 m0, s53
	s_branch .Ld2_skip

.Ld2_skip:
	s_waitcnt lgkmcnt(13)
	v_mfma_f32_32x32x16_bf16 v[80:95], v[144:147], v[184:187], v[64:79]
	v_exp_f32_e32 v112, v112
	v_exp_f32_e32 v113, v113
	v_add_f32_e32 v244, v244, v112
	v_add_f32_e32 v244, v244, v113
	v_cvt_pk_bf16_f32 v112, v112, v113
	v_mfma_f32_32x32x16_bf16 v[96:111], v[144:147], v[200:203], v[64:79]
	ds_read_b128 v[144:147], v242 offset:18432
	v_exp_f32_e32 v114, v114
	v_exp_f32_e32 v115, v115
	v_add_f32_e32 v244, v244, v114
	v_add_f32_e32 v244, v244, v115
	v_cvt_pk_bf16_f32 v113, v114, v115
	s_waitcnt lgkmcnt(13)
	v_mfma_f32_32x32x16_bf16 v[80:95], v[148:151], v[188:191], v[80:95]
	v_exp_f32_e32 v116, v116
	v_exp_f32_e32 v117, v117
	v_add_f32_e32 v244, v244, v116
	v_add_f32_e32 v244, v244, v117
	v_cvt_pk_bf16_f32 v114, v116, v117
	v_mfma_f32_32x32x16_bf16 v[96:111], v[148:151], v[204:207], v[96:111]
	ds_read_b128 v[148:151], v242 offset:19456
	v_exp_f32_e32 v118, v118
	v_exp_f32_e32 v119, v119
	v_add_f32_e32 v244, v244, v118
	v_add_f32_e32 v244, v244, v119
	s_waitcnt lgkmcnt(13)
	v_mfma_f32_32x32x16_bf16 v[80:95], v[152:155], v[192:195], v[80:95]
	v_cvt_pk_bf16_f32 v115, v118, v119
	v_exp_f32_e32 v128, v128
	v_exp_f32_e32 v129, v129
	v_add_f32_e32 v245, v245, v128
	v_mfma_f32_32x32x16_bf16 v[96:111], v[152:155], v[208:211], v[96:111]
	ds_read_b128 v[152:155], v242 offset:20480
	v_add_f32_e32 v245, v245, v129
	v_cvt_pk_bf16_f32 v128, v128, v129
	v_exp_f32_e32 v130, v130
	v_exp_f32_e32 v131, v131
	s_waitcnt lgkmcnt(9)
	v_mfma_f32_32x32x16_bf16 v[48:63], v[112:115], v[168:171], v[48:63]
	v_add_f32_e32 v245, v245, v130
	v_add_f32_e32 v245, v245, v131
	v_cvt_pk_bf16_f32 v129, v130, v131
	v_exp_f32_e32 v132, v132
	v_exp_f32_e32 v133, v133
	v_mfma_f32_32x32x16_bf16 v[80:95], v[156:159], v[196:199], v[80:95]
	v_add_f32_e32 v245, v245, v132
	v_add_f32_e32 v245, v245, v133
	v_cvt_pk_bf16_f32 v130, v132, v133
	v_exp_f32_e32 v134, v134
	v_exp_f32_e32 v135, v135
	s_waitcnt lgkmcnt(7)
	v_mfma_f32_32x32x16_bf16 v[32:47], v[112:115], v[176:179], v[32:47]
	v_add_f32_e32 v245, v245, v134
	v_add_f32_e32 v245, v245, v135
	v_cvt_pk_bf16_f32 v131, v134, v135
	v_exp_f32_e32 v120, v120
	v_mfma_f32_32x32x16_bf16 v[96:111], v[156:159], v[212:215], v[96:111]
	ds_read_b128 v[156:159], v242 offset:21504
	v_exp_f32_e32 v121, v121
	v_add_f32_e32 v244, v244, v120
	v_add_f32_e32 v244, v244, v121
	v_cvt_pk_bf16_f32 v120, v120, v121
	v_mfma_f32_32x32x16_bf16 v[80:95], v[160:163], v[216:219], v[80:95]
	v_exp_f32_e32 v122, v122
	v_exp_f32_e32 v123, v123
	v_add_f32_e32 v244, v244, v122
	v_add_f32_e32 v244, v244, v123
	v_cvt_pk_bf16_f32 v121, v122, v123
	v_mfma_f32_32x32x16_bf16 v[96:111], v[160:163], v[224:227], v[96:111]
	ds_read_b128 v[160:163], v242 offset:22528
	v_exp_f32_e32 v124, v124
	v_exp_f32_e32 v125, v125
	v_add_f32_e32 v244, v244, v124
	v_add_f32_e32 v244, v244, v125
	v_cvt_pk_bf16_f32 v122, v124, v125
	v_mfma_f32_32x32x16_bf16 v[16:31], v[128:131], v[168:171], v[16:31]
	v_exp_f32_e32 v126, v126
	v_exp_f32_e32 v127, v127
	v_add_f32_e32 v244, v244, v126
	v_add_f32_e32 v244, v244, v127
	v_mfma_f32_32x32x16_bf16 v[80:95], v[164:167], v[220:223], v[80:95]
	v_cvt_pk_bf16_f32 v123, v126, v127
	v_exp_f32_e32 v136, v136
	v_exp_f32_e32 v137, v137
	v_add_f32_e32 v245, v245, v136
	v_mfma_f32_32x32x16_bf16 v[0:15], v[128:131], v[176:179], v[0:15]
	v_add_f32_e32 v245, v245, v137
	v_cvt_pk_bf16_f32 v136, v136, v137
	v_exp_f32_e32 v138, v138
	v_exp_f32_e32 v139, v139
	v_add_f32_e32 v245, v245, v138
	v_mfma_f32_32x32x16_bf16 v[96:111], v[164:167], v[228:231], v[96:111]
	ds_read_b128 v[164:167], v242 offset:23552
	v_add_f32_e32 v245, v245, v139
	v_cvt_pk_bf16_f32 v137, v138, v139
	v_exp_f32_e32 v140, v140
	v_exp_f32_e32 v141, v141
	v_add_f32_e32 v245, v245, v140
	s_waitcnt lgkmcnt(8)
	v_mfma_f32_32x32x16_bf16 v[48:63], v[120:123], v[172:175], v[48:63]
	v_add_f32_e32 v245, v245, v141
	v_cvt_pk_bf16_f32 v138, v140, v141
	v_exp_f32_e32 v142, v142
	v_exp_f32_e32 v143, v143
	s_waitcnt lgkmcnt(6)
	v_mfma_f32_32x32x16_bf16 v[32:47], v[120:123], v[180:183], v[32:47]
	v_add_f32_e32 v245, v245, v142
	v_add_f32_e32 v245, v245, v143
	v_cvt_pk_bf16_f32 v139, v142, v143
	ds_read_b64_tr_b16 v[168:169], v241 offset:57344
	ds_read_b64_tr_b16 v[170:171], v241 offset:58368
	ds_read_b64_tr_b16 v[176:177], v232 offset:57344
	ds_read_b64_tr_b16 v[178:179], v232 offset:58368
	v_mfma_f32_32x32x16_bf16 v[16:31], v[136:139], v[172:175], v[16:31]
	ds_read_b64_tr_b16 v[172:173], v241 offset:59392
	ds_read_b64_tr_b16 v[174:175], v241 offset:60416
	v_mfma_f32_32x32x16_bf16 v[0:15], v[136:139], v[180:183], v[0:15]
	ds_read_b64_tr_b16 v[180:181], v232 offset:59392
	ds_read_b64_tr_b16 v[182:183], v232 offset:60416
	s_waitcnt lgkmcnt(13)
	v_mfma_f32_32x32x16_bf16 v[112:127], v[144:147], v[184:187], v[64:79]
	v_exp_f32_e32 v80, v80
	v_exp_f32_e32 v81, v81
	v_add_f32_e32 v244, v244, v80
	v_add_f32_e32 v244, v244, v81
	v_cvt_pk_bf16_f32 v80, v80, v81
	v_mfma_f32_32x32x16_bf16 v[128:143], v[144:147], v[200:203], v[64:79]
	v_exp_f32_e32 v82, v82
	v_exp_f32_e32 v83, v83
	v_add_f32_e32 v244, v244, v82
	v_add_f32_e32 v244, v244, v83
	v_cvt_pk_bf16_f32 v81, v82, v83
	s_waitcnt lgkmcnt(12)
	v_mfma_f32_32x32x16_bf16 v[112:127], v[148:151], v[188:191], v[112:127]
	v_exp_f32_e32 v84, v84
	v_exp_f32_e32 v85, v85
	v_add_f32_e32 v244, v244, v84
	v_add_f32_e32 v244, v244, v85
	v_cvt_pk_bf16_f32 v82, v84, v85
	v_mfma_f32_32x32x16_bf16 v[128:143], v[148:151], v[204:207], v[128:143]
	v_exp_f32_e32 v86, v86
	v_exp_f32_e32 v87, v87
	v_add_f32_e32 v244, v244, v86
	v_add_f32_e32 v244, v244, v87
	s_waitcnt lgkmcnt(11)
	v_mfma_f32_32x32x16_bf16 v[112:127], v[152:155], v[192:195], v[112:127]
	v_cvt_pk_bf16_f32 v83, v86, v87
	v_exp_f32_e32 v96, v96
	v_exp_f32_e32 v97, v97
	v_add_f32_e32 v245, v245, v96
	v_mfma_f32_32x32x16_bf16 v[128:143], v[152:155], v[208:211], v[128:143]
	v_add_f32_e32 v245, v245, v97
	v_cvt_pk_bf16_f32 v96, v96, v97
	v_exp_f32_e32 v98, v98
	v_exp_f32_e32 v99, v99
	s_waitcnt lgkmcnt(6)
	v_mfma_f32_32x32x16_bf16 v[48:63], v[80:83], v[168:171], v[48:63]
	v_add_f32_e32 v245, v245, v98
	v_add_f32_e32 v245, v245, v99
	v_cvt_pk_bf16_f32 v97, v98, v99
	v_exp_f32_e32 v100, v100
	v_exp_f32_e32 v101, v101
	v_mfma_f32_32x32x16_bf16 v[112:127], v[156:159], v[196:199], v[112:127]
	v_add_f32_e32 v245, v245, v100
	v_add_f32_e32 v245, v245, v101
	v_cvt_pk_bf16_f32 v98, v100, v101
	v_exp_f32_e32 v102, v102
	v_exp_f32_e32 v103, v103
	s_waitcnt lgkmcnt(4)
	v_mfma_f32_32x32x16_bf16 v[32:47], v[80:83], v[176:179], v[32:47]
	v_add_f32_e32 v245, v245, v102
	v_add_f32_e32 v245, v245, v103
	v_cvt_pk_bf16_f32 v99, v102, v103
	v_exp_f32_e32 v88, v88
	v_mfma_f32_32x32x16_bf16 v[128:143], v[156:159], v[212:215], v[128:143]
	v_exp_f32_e32 v89, v89
	v_add_f32_e32 v244, v244, v88
	v_add_f32_e32 v244, v244, v89
	v_cvt_pk_bf16_f32 v88, v88, v89
	v_mfma_f32_32x32x16_bf16 v[112:127], v[160:163], v[216:219], v[112:127]
	v_exp_f32_e32 v90, v90
	v_exp_f32_e32 v91, v91
	v_add_f32_e32 v244, v244, v90
	v_add_f32_e32 v244, v244, v91
	v_cvt_pk_bf16_f32 v89, v90, v91
	v_mfma_f32_32x32x16_bf16 v[128:143], v[160:163], v[224:227], v[128:143]
	v_exp_f32_e32 v92, v92
	v_exp_f32_e32 v93, v93
	v_add_f32_e32 v244, v244, v92
	v_add_f32_e32 v244, v244, v93
	v_cvt_pk_bf16_f32 v90, v92, v93
	v_mfma_f32_32x32x16_bf16 v[16:31], v[96:99], v[168:171], v[16:31]
	v_exp_f32_e32 v94, v94
	v_exp_f32_e32 v95, v95
	v_add_f32_e32 v244, v244, v94
	v_add_f32_e32 v244, v244, v95
	v_mfma_f32_32x32x16_bf16 v[112:127], v[164:167], v[220:223], v[112:127]
	v_cvt_pk_bf16_f32 v91, v94, v95
	v_exp_f32_e32 v104, v104
	v_exp_f32_e32 v105, v105
	v_add_f32_e32 v245, v245, v104
	v_mfma_f32_32x32x16_bf16 v[0:15], v[96:99], v[176:179], v[0:15]
	v_add_f32_e32 v245, v245, v105
	v_cvt_pk_bf16_f32 v104, v104, v105
	v_exp_f32_e32 v106, v106
	v_exp_f32_e32 v107, v107
	v_add_f32_e32 v245, v245, v106
	v_mfma_f32_32x32x16_bf16 v[128:143], v[164:167], v[228:231], v[128:143]
	v_add_f32_e32 v245, v245, v107
	v_cvt_pk_bf16_f32 v105, v106, v107
	v_exp_f32_e32 v108, v108
	v_exp_f32_e32 v109, v109
	v_add_f32_e32 v245, v245, v108
	s_waitcnt lgkmcnt(2)
	v_mfma_f32_32x32x16_bf16 v[48:63], v[88:91], v[172:175], v[48:63]
	v_add_f32_e32 v245, v245, v109
	v_cvt_pk_bf16_f32 v106, v108, v109
	v_exp_f32_e32 v110, v110
	v_exp_f32_e32 v111, v111
	s_waitcnt lgkmcnt(0)
	v_mfma_f32_32x32x16_bf16 v[32:47], v[88:91], v[180:183], v[32:47]
	v_add_f32_e32 v245, v245, v110
	v_add_f32_e32 v245, v245, v111
	v_cvt_pk_bf16_f32 v107, v110, v111
	ds_read_b64_tr_b16 v[168:169], v241 offset:61440
	ds_read_b64_tr_b16 v[170:171], v241 offset:62464
	ds_read_b64_tr_b16 v[176:177], v232 offset:61440
	ds_read_b64_tr_b16 v[178:179], v232 offset:62464
	v_mfma_f32_32x32x16_bf16 v[16:31], v[104:107], v[172:175], v[16:31]
	ds_read_b64_tr_b16 v[172:173], v241 offset:63488
	ds_read_b64_tr_b16 v[174:175], v241 offset:64512
	v_mfma_f32_32x32x16_bf16 v[0:15], v[104:107], v[180:183], v[0:15]
	ds_read_b64_tr_b16 v[180:181], v232 offset:63488
	ds_read_b64_tr_b16 v[182:183], v232 offset:64512
	s_waitcnt vmcnt(0)
	s_waitcnt lgkmcnt(0)
	s_barrier
	s_cmp_eq_u32 s28, 64
	s_cbranch_scc1 .Lmla_last
	s_and_b32 s12, s28, 1
	s_mul_i32 s13, s12, 0x6000
	v_add_u32_e32 v242, s13, v237
	v_lshl_add_u32 v241, s12, 14, v238
	v_add_u32_e32 v232, v241, v240
	v_add_u32_e32 v241, v241, v239
	ds_read_b128 v[144:147], v242
	ds_read_b128 v[148:151], v242 offset:1024
	ds_read_b128 v[152:155], v242 offset:2048
	ds_read_b128 v[156:159], v242 offset:3072
	ds_read_b128 v[160:163], v242 offset:4096
	ds_read_b128 v[164:167], v242 offset:5120
	v_exp_f32_e32 v112, v112
	v_exp_f32_e32 v113, v113
	v_add_f32_e32 v244, v244, v112
	v_add_f32_e32 v244, v244, v113
	v_cvt_pk_bf16_f32 v112, v112, v113
	v_exp_f32_e32 v114, v114
	v_exp_f32_e32 v115, v115
	v_add_f32_e32 v244, v244, v114
	v_add_f32_e32 v244, v244, v115
	v_cvt_pk_bf16_f32 v113, v114, v115
	s_waitcnt lgkmcnt(5)
	v_mfma_f32_32x32x16_bf16 v[80:95], v[144:147], v[184:187], v[64:79]
	v_exp_f32_e32 v116, v116
	v_exp_f32_e32 v117, v117
	v_add_f32_e32 v244, v244, v116
	v_add_f32_e32 v244, v244, v117
	v_mfma_f32_32x32x16_bf16 v[96:111], v[144:147], v[200:203], v[64:79]
	ds_read_b128 v[144:147], v242 offset:6144
	v_cvt_pk_bf16_f32 v114, v116, v117
	v_exp_f32_e32 v118, v118
	v_exp_f32_e32 v119, v119
	v_add_f32_e32 v244, v244, v118
	s_waitcnt lgkmcnt(5)
	v_mfma_f32_32x32x16_bf16 v[80:95], v[148:151], v[188:191], v[80:95]
	v_add_f32_e32 v244, v244, v119
	v_cvt_pk_bf16_f32 v115, v118, v119
	v_exp_f32_e32 v128, v128
	v_exp_f32_e32 v129, v129
	v_mfma_f32_32x32x16_bf16 v[96:111], v[148:151], v[204:207], v[96:111]
	ds_read_b128 v[148:151], v242 offset:7168
	v_add_f32_e32 v245, v245, v128
	v_add_f32_e32 v245, v245, v129
	v_cvt_pk_bf16_f32 v128, v128, v129
	v_exp_f32_e32 v130, v130
	s_waitcnt lgkmcnt(5)
	v_mfma_f32_32x32x16_bf16 v[80:95], v[152:155], v[192:195], v[80:95]
	v_exp_f32_e32 v131, v131
	v_add_f32_e32 v245, v245, v130
	v_add_f32_e32 v245, v245, v131
	v_cvt_pk_bf16_f32 v129, v130, v131
	v_mfma_f32_32x32x16_bf16 v[96:111], v[152:155], v[208:211], v[96:111]
	ds_read_b128 v[152:155], v242 offset:8192
	v_exp_f32_e32 v132, v132
	v_exp_f32_e32 v133, v133
	v_add_f32_e32 v245, v245, v132
	v_add_f32_e32 v245, v245, v133
	v_mfma_f32_32x32x16_bf16 v[48:63], v[112:115], v[168:171], v[48:63]
	v_cvt_pk_bf16_f32 v130, v132, v133
	v_exp_f32_e32 v134, v134
	v_exp_f32_e32 v135, v135
	v_add_f32_e32 v245, v245, v134
	s_waitcnt lgkmcnt(5)
	v_mfma_f32_32x32x16_bf16 v[80:95], v[156:159], v[196:199], v[80:95]
	v_add_f32_e32 v245, v245, v135
	v_cvt_pk_bf16_f32 v131, v134, v135
	v_exp_f32_e32 v120, v120
	v_exp_f32_e32 v121, v121
	v_mfma_f32_32x32x16_bf16 v[32:47], v[112:115], v[176:179], v[32:47]
	v_add_f32_e32 v244, v244, v120
	v_add_f32_e32 v244, v244, v121
	v_cvt_pk_bf16_f32 v120, v120, v121
	v_exp_f32_e32 v122, v122
	v_mfma_f32_32x32x16_bf16 v[96:111], v[156:159], v[212:215], v[96:111]
	ds_read_b128 v[156:159], v242 offset:9216
	v_exp_f32_e32 v123, v123
	v_add_f32_e32 v244, v244, v122
	v_add_f32_e32 v244, v244, v123
	v_cvt_pk_bf16_f32 v121, v122, v123
	s_waitcnt lgkmcnt(5)
	v_mfma_f32_32x32x16_bf16 v[80:95], v[160:163], v[216:219], v[80:95]
	v_exp_f32_e32 v124, v124
	v_exp_f32_e32 v125, v125
	v_add_f32_e32 v244, v244, v124
	v_add_f32_e32 v244, v244, v125
	v_mfma_f32_32x32x16_bf16 v[96:111], v[160:163], v[224:227], v[96:111]
	ds_read_b128 v[160:163], v242 offset:10240
	v_cvt_pk_bf16_f32 v122, v124, v125
	v_exp_f32_e32 v126, v126
	v_exp_f32_e32 v127, v127
	v_add_f32_e32 v244, v244, v126
	v_mfma_f32_32x32x16_bf16 v[16:31], v[128:131], v[168:171], v[16:31]
	v_add_f32_e32 v244, v244, v127
	v_cvt_pk_bf16_f32 v123, v126, v127
	v_exp_f32_e32 v136, v136
	v_exp_f32_e32 v137, v137
	s_waitcnt lgkmcnt(5)
	v_mfma_f32_32x32x16_bf16 v[80:95], v[164:167], v[220:223], v[80:95]
	v_add_f32_e32 v245, v245, v136
	v_add_f32_e32 v245, v245, v137
	v_cvt_pk_bf16_f32 v136, v136, v137
	v_exp_f32_e32 v138, v138
	v_mfma_f32_32x32x16_bf16 v[0:15], v[128:131], v[176:179], v[0:15]
	v_exp_f32_e32 v139, v139
	v_add_f32_e32 v245, v245, v138
	v_add_f32_e32 v245, v245, v139
	v_cvt_pk_bf16_f32 v137, v138, v139
	v_mfma_f32_32x32x16_bf16 v[96:111], v[164:167], v[228:231], v[96:111]
	ds_read_b128 v[164:167], v242 offset:11264
	v_exp_f32_e32 v140, v140
	v_exp_f32_e32 v141, v141
	v_add_f32_e32 v245, v245, v140
	v_add_f32_e32 v245, v245, v141
	v_mfma_f32_32x32x16_bf16 v[48:63], v[120:123], v[172:175], v[48:63]
	v_cvt_pk_bf16_f32 v138, v140, v141
	v_exp_f32_e32 v142, v142
	v_exp_f32_e32 v143, v143
	v_mfma_f32_32x32x16_bf16 v[32:47], v[120:123], v[180:183], v[32:47]
	v_add_f32_e32 v245, v245, v142
	v_add_f32_e32 v245, v245, v143
	v_cvt_pk_bf16_f32 v139, v142, v143
	ds_read_b64_tr_b16 v[168:169], v241 offset:49152
	ds_read_b64_tr_b16 v[170:171], v241 offset:50176
	ds_read_b64_tr_b16 v[176:177], v232 offset:49152
	ds_read_b64_tr_b16 v[178:179], v232 offset:50176
	v_mfma_f32_32x32x16_bf16 v[16:31], v[136:139], v[172:175], v[16:31]
	ds_read_b64_tr_b16 v[172:173], v241 offset:51200
	ds_read_b64_tr_b16 v[174:175], v241 offset:52224
	v_mfma_f32_32x32x16_bf16 v[0:15], v[136:139], v[180:183], v[0:15]
	ds_read_b64_tr_b16 v[180:181], v232 offset:51200
	ds_read_b64_tr_b16 v[182:183], v232 offset:52224
	s_branch .Lmla_tail
